# deferred-rendezvous barriers: L2 write-back and cross-XCD arrival delegated to the workgroup with one tile fewer in the next phase (off the last arriver's path)
# baseline (speedup 1.0000x reference)
.LBB0_92:
	s_or_b64 exec, exec, s[0:1]
	v_readlane_b32 s12, v255, 40
	s_nop 1
	s_cmp_lg_u32 s12, 0
	s_cselect_b32 s13, 3, 0
	s_nop 0
	v_writelane_b32 v255, s13, 41
	v_readlane_b32 s12, v255, 40
	s_nop 1
	s_cmp_eq_u32 s12, 0
	s_cbranch_scc1 .Lxg4_skip
	s_and_b32 s12, s84, 31
	s_cmp_lg_u32 s12, 31
	s_cbranch_scc1 .Lxg4_skip
	v_cmp_eq_u32_e32 vcc, 0, v247
	s_and_saveexec_b64 s[12:13], vcc
	s_cbranch_execz .Lxg4_r
	buffer_wbl2 sc1
	s_waitcnt vmcnt(0)
	v_readlane_b32 s14, v254, 18
	v_readlane_b32 s15, v254, 19
	v_mov_b32_e32 v0, 1
	s_nop 4
	global_atomic_add v0, v1, v0, s[14:15] sc0
	s_waitcnt vmcnt(0)
	v_add_u32_e32 v0, 1, v0
	v_and_b32_e32 v0, 7, v0
	v_cmp_eq_u32_e32 vcc, 0, v0
	s_cbranch_vccz .Lxg4_r
	v_readlane_b32 s14, v254, 20
	v_readlane_b32 s15, v254, 21
	v_mov_b32_e32 v0, 1
	s_nop 4
	global_atomic_add v1, v0, s[14:15]
	s_waitcnt vmcnt(0)
.Lxg4_r:
	s_or_b64 exec, exec, s[12:13]
.Lxg4_skip:
	s_mov_b64 s[0:1], 0
	s_waitcnt lgkmcnt(0)
	s_barrier

.LBB0_505:
	s_andn2_saveexec_b64 s[4:5], s[4:5]
	s_cbranch_execz .LBB0_525
	s_mov_b64 s[4:5], exec
	v_readlane_b32 s12, v255, 40
	s_nop 1
	s_cmp_eq_u32 s12, 0
	s_cbranch_scc1 .Lxd2_glob
	v_readlane_b32 s12, v254, 16
	v_readlane_b32 s13, v254, 17
	v_mov_b32_e32 v0, 1
	s_nop 4
	global_atomic_add v1, v0, s[12:13]
	s_branch .LBB0_525

.LBB0_525:
	s_or_b64 exec, exec, s[0:1]
	v_readlane_b32 s12, v255, 40
	s_lshl_b32 s13, s52, 1
	s_add_i32 s13, s13, 2
	s_cmp_lg_u32 s12, 0
	s_cselect_b32 s13, s13, 0
	s_nop 0
	v_writelane_b32 v255, s13, 41
	v_readlane_b32 s12, v255, 40
	s_nop 1
	s_cmp_eq_u32 s12, 0
	s_cbranch_scc1 .Lxg2_skip
	s_and_b32 s12, s84, 31
	s_cmp_lg_u32 s12, 31
	s_cbranch_scc1 .Lxg2_skip
	v_cmp_eq_u32_e32 vcc, 0, v247
	s_and_saveexec_b64 s[12:13], vcc
	s_cbranch_execz .Lxg2_r
	buffer_wbl2 sc1
	s_waitcnt vmcnt(0)
	v_readlane_b32 s14, v254, 18
	v_readlane_b32 s15, v254, 19
	v_mov_b32_e32 v0, 1
	s_nop 4
	global_atomic_add v0, v1, v0, s[14:15] sc0
	s_waitcnt vmcnt(0)
	v_add_u32_e32 v0, 1, v0
	v_and_b32_e32 v0, 7, v0
	v_cmp_eq_u32_e32 vcc, 0, v0
	s_cbranch_vccz .Lxg2_r
	v_readlane_b32 s14, v254, 20
	v_readlane_b32 s15, v254, 21
	v_mov_b32_e32 v0, 1
	s_nop 4
	global_atomic_add v1, v0, s[14:15]
	s_waitcnt vmcnt(0)

.Lxg2_skip:
	v_readlane_b32 s0, v254, 28
	s_mov_b64 s[4:5], s[62:63]
	v_mov_b32_e32 v10, v247
	v_readlane_b32 s1, v254, 29
	s_waitcnt lgkmcnt(0)
	s_barrier
	s_mul_i32 s22, s52, 0x2100
	s_mov_b32 s23, s59
	s_andn2_b64 vcc, exec, s[0:1]
	v_readfirstlane_b32 s6, v10
	s_cbranch_vccnz .LBB0_730
	v_lshlrev_b32_e32 v0, 4, v10
	v_add_u32_e32 v2, 0x2000, v0
	v_ashrrev_i32_e32 v3, 31, v2
	v_lshrrev_b32_e32 v3, 22, v3
	v_add_u32_e32 v3, v2, v3
	v_ashrrev_i32_e32 v11, 10, v3
	v_mul_i32_i24_e32 v3, 0x400, v11
	v_sub_u32_e32 v2, v2, v3
	v_lshrrev_b32_e32 v3, 4, v2
	v_bitop3_b32 v2, v3, v2, 32 bitop3:0x6c
	v_ashrrev_i32_e32 v3, 31, v2
	v_lshrrev_b32_e32 v3, 26, v3
	v_add_u32_e32 v3, v2, v3
	v_lshlrev_b32_e32 v4, 3, v11
	v_ashrrev_i32_e32 v12, 6, v3
	v_and_b32_e32 v4, -16, v4
	v_add_u32_e32 v4, v12, v4
	v_and_b32_e32 v5, 3, v12
	v_lshrrev_b32_e32 v6, 2, v4
	v_lshlrev_b32_e32 v7, 1, v4
	v_and_or_b32 v5, v4, s97, v5
	v_and_b32_e32 v6, 4, v6
	v_and_b32_e32 v7, 24, v7
	v_and_b32_e32 v3, 0xc0, v3
	v_or3_b32 v5, v5, v6, v7
	v_sub_u32_e32 v2, v2, v3
	v_mov_b32_e32 v7, 1
	v_lshlrev_b32_e32 v6, 5, v11
	v_ashrrev_i16_sdwa v2, v7, sext(v2) dst_sel:DWORD dst_unused:UNUSED_PAD src0_sel:DWORD src1_sel:BYTE_0
	v_and_b32_e32 v6, 32, v6
	v_bfe_i32 v13, v2, 0, 16
	v_add_lshl_u32 v2, v6, v13, 1
	v_lshl_add_u32 v156, v5, 11, v2
	v_lshl_add_u32 v158, v4, 11, v2
	v_bfe_i32 v2, v10, 27, 1
	v_lshrrev_b32_e32 v2, 22, v2
	v_add_u32_e32 v2, v0, v2
	s_load_dwordx2 s[0:1], s[4:5], 0xa0
	v_and_b32_e32 v2, 0xfffffc00, v2
	v_sub_u32_e32 v0, v0, v2
	v_lshrrev_b32_e32 v2, 4, v0
	v_ashrrev_i32_e32 v3, 31, v10
	v_bitop3_b32 v0, v2, v0, 32 bitop3:0x6c
	v_lshrrev_b32_e32 v3, 26, v3
	v_ashrrev_i32_e32 v2, 31, v0
	v_add_u32_e32 v3, v10, v3
	s_waitcnt lgkmcnt(0)
	s_add_u32 s70, s0, 0x3000000
	v_lshrrev_b32_e32 v2, 26, v2
	v_ashrrev_i32_e32 v15, 6, v3
	s_mov_b32 s93, s3
	s_addc_u32 s71, s1, 0
	s_mul_i32 s3, s52, 0x1700000
	v_add_u32_e32 v2, v0, v2
	v_lshlrev_b32_e32 v3, 3, v15
	s_load_dwordx4 s[44:47], s[4:5], 0x80
	s_add_u32 s4, s0, s3
	v_ashrrev_i32_e32 v14, 6, v2
	v_and_b32_e32 v3, -16, v3
	s_addc_u32 s5, s1, 0
	v_add_u32_e32 v3, v14, v3
	s_add_u32 s72, s4, 0x880000
	v_and_b32_e32 v4, 3, v14
	v_lshrrev_b32_e32 v5, 2, v3
	v_lshlrev_b32_e32 v6, 1, v3
	v_and_b32_e32 v2, 0xc0, v2
	s_addc_u32 s73, s5, 0
	s_ashr_i32 s5, s6, 6
	v_and_or_b32 v4, v3, s97, v4
	v_and_b32_e32 v5, 4, v5
	v_and_b32_e32 v6, 24, v6
	v_sub_u32_e32 v0, v0, v2
	s_ashr_i32 s4, s6, 8
	s_lshl_b32 s64, s5, 10
	v_or3_b32 v4, v4, v5, v6
	v_lshlrev_b32_e32 v5, 5, v15
	v_ashrrev_i16_sdwa v0, v7, sext(v0) dst_sel:DWORD dst_unused:UNUSED_PAD src0_sel:DWORD src1_sel:BYTE_0
	v_readlane_b32 s8, v254, 36
	v_and_b32_e32 v5, 32, v5
	v_bfe_i32 v16, v0, 0, 16
	v_readlane_b32 s9, v254, 37
	s_add_u32 s48, s72, s8
	v_add_lshl_u32 v2, v5, v16, 1
	s_addc_u32 s49, s73, s9
	s_add_i32 s65, s64, 0
	v_lshl_add_u32 v0, v4, 11, v2
	s_add_i32 m0, s65, 0x10000
	v_lshl_add_u32 v160, v3, 11, v2
	global_load_lds_dwordx4 v0, s[48:49]
	s_add_i32 m0, s65, 0x12000
	s_add_u32 s8, s48, 0x40000
	global_load_lds_dwordx4 v156, s[48:49]
	s_addc_u32 s9, s49, 0
	s_add_i32 m0, s65, 0x14000
	v_mov_b32_e32 v157, v1
	global_load_lds_dwordx4 v0, s[8:9]
	s_add_i32 m0, s65, 0x16000
	v_mov_b32_e32 v161, v1
	global_load_lds_dwordx4 v156, s[8:9]
	v_readlane_b32 s8, v254, 50
	v_readlane_b32 s9, v254, 51
	s_add_u32 s50, s70, s8
	s_addc_u32 s51, s71, s9
	s_add_i32 s66, s65, 0x2000
	s_mov_b32 m0, s65
	s_add_u32 s8, s50, 0x40000
	global_load_lds_dwordx4 v160, s[50:51]
	s_mov_b32 m0, s66
	s_addc_u32 s9, s51, 0
	s_add_i32 s67, s65, 0x4000
	global_load_lds_dwordx4 v158, s[50:51]
	s_mov_b32 m0, s67
	s_add_i32 s68, s65, 0x6000
	global_load_lds_dwordx4 v160, s[8:9]
	s_mov_b32 m0, s68
	s_cmp_eq_u32 s4, 1
	global_load_lds_dwordx4 v158, s[8:9]
	s_cselect_b64 s[8:9], -1, 0
	v_mov_b32_e32 v159, v1
	v_writelane_b32 v255, s8, 16
	v_lshl_add_u64 v[6:7], s[48:49], 0, v[0:1]
	v_lshl_add_u64 v[4:5], s[48:49], 0, v[156:157]
	v_lshl_add_u64 v[2:3], s[50:51], 0, v[160:161]
	v_writelane_b32 v255, s9, 17
	s_cmp_lg_u32 s4, 1
	v_lshl_add_u64 v[8:9], s[50:51], 0, v[158:159]
	s_cbranch_scc1 .LBB0_528
	s_barrier
